# P5 epilogue loads of gates/tmpb (read once) marked nt, on top of the P0 nt loads
# speedup vs baseline: 1.0420x; 1.0003x over previous
; __device__ __forceinline__ unsigned pk_bf16(float lo, float hi) { typedef __bf16 b2 __attribute__((ext_vector_type(2))); f32x2 v = {lo, hi}; b2 b = __builtin_convertvector(v, b2); return __builtin_bit_cast(unsigned, b); }
; __device__ __forceinline__ float bflo(unsigned u) { return __uint_as_float(u << 16); }
; __device__ __forceinline__ float bfhi(unsigned u) { return __uint_as_float(u & 0xffff0000u); }
;     __device__ __forceinline__ void operator()(const f32x4 (&acc)[2][2][4][2], const Unit& u, int wr, int wc, int fr, int fq) const {
;         const int row0 = u.pm * 256 + wr * 64 + fr, col0 = u.pn * 256 + wc * 32 + 8 * fq;
; #pragma unroll
;         for (int ai = 0; ai < 2; ++ai) { u32x4 gg[4][2], tb[4][2];
; #pragma unroll
;             for (int m = 0; m < 4; ++m)
; #pragma unroll
;                 for (int bj = 0; bj < 2; ++bj) { const size_t row = row0 + ai * 128 + m * 16; gg[m][bj] = *(const u32x4*)(gates + row * 2048 + col0 + bj * 128); tb[m][bj] = *(const u32x4*)(tmpb + row * 1024 + col0 + bj * 128); }
; #pragma unroll
;             for (int m = 0; m < 4; ++m) { const size_t row = row0 + ai * 128 + m * 16;
; #pragma unroll
;                 for (int bj = 0; bj < 2; ++bj) { const int col = col0 + bj * 128; const u32x4 g = gg[m][bj], t = tb[m][bj];
;                     const f32x4 v0 = acc[ai][bj][m][0], v1 = acc[ai][bj][m][1]; u32x4 w;
;                     w.x = pk_bf16(bflo(t.x) + v0[0] * bflo(g.x), bfhi(t.x) + v0[1] * bfhi(g.x)); w.y = pk_bf16(bflo(t.y) + v0[2] * bflo(g.y), bfhi(t.y) + v0[3] * bfhi(g.y));
;                     w.z = pk_bf16(bflo(t.z) + v1[0] * bflo(g.z), bfhi(t.z) + v1[1] * bfhi(g.z)); w.w = pk_bf16(bflo(t.w) + v1[2] * bflo(g.w), bfhi(t.w) + v1[3] * bfhi(g.w));
;                     *(u32x4*)(merged + row * 1024 + col) = w; } } }
.LBB0_607:
	v_lshl_or_b32 v128, s52, 8, v182
	v_lshl_add_u32 v172, s26, 8, v180
	v_ashrrev_i32_e32 v129, 31, v128
	v_lshlrev_b64 v[168:169], 1, v[128:129]
	v_ashrrev_i32_e32 v173, 31, v172
	v_lshl_add_u64 v[170:171], s[10:11], 0, v[168:169]
	v_lshlrev_b64 v[130:131], 11, v[172:173]
	v_lshl_add_u64 v[174:175], s[8:9], 0, v[168:169]
	v_lshlrev_b64 v[128:129], 12, v[172:173]
	v_lshl_add_u64 v[132:133], v[170:171], 0, v[130:131]
	global_load_dwordx4 v[190:193], v[132:133], off nt
	v_lshl_add_u64 v[128:129], v[174:175], 0, v[128:129]
	global_load_dwordx4 v[194:197], v[128:129], off nt
	global_load_dwordx4 v[198:201], v[132:133], off offset:256 nt
	global_load_dwordx4 v[202:205], v[128:129], off offset:256 nt
	v_or_b32_e32 v128, 16, v172
	v_ashrrev_i32_e32 v129, 31, v128
	v_lshlrev_b64 v[132:133], 12, v[128:129]
	v_lshlrev_b64 v[186:187], 11, v[128:129]
	v_lshl_add_u64 v[128:129], v[170:171], 0, v[186:187]
	v_lshl_add_u64 v[132:133], v[174:175], 0, v[132:133]
	global_load_dwordx4 v[206:209], v[128:129], off nt
	global_load_dwordx4 v[210:213], v[132:133], off nt
	v_or_b32_e32 v134, 32, v172
	v_or_b32_e32 v136, 48, v172
	v_ashrrev_i32_e32 v135, 31, v134
	v_ashrrev_i32_e32 v137, 31, v136
	v_lshlrev_b64 v[138:139], 12, v[134:135]
	v_lshlrev_b64 v[178:179], 11, v[134:135]
	v_lshlrev_b64 v[134:135], 12, v[136:137]
	v_lshlrev_b64 v[176:177], 11, v[136:137]
	v_lshl_add_u64 v[130:131], s[12:13], 0, v[130:131]
	v_lshl_add_u64 v[136:137], v[174:175], 0, v[138:139]
	v_lshl_add_u64 v[138:139], v[170:171], 0, v[178:179]
	v_lshl_add_u64 v[134:135], v[174:175], 0, v[134:135]
	v_lshl_add_u64 v[230:231], v[170:171], 0, v[176:177]
	v_lshl_add_u64 v[232:233], v[130:131], 0, v[168:169]
	global_load_dwordx4 v[214:217], v[132:133], off offset:256 nt
	global_load_dwordx4 v[218:221], v[128:129], off offset:256 nt
	global_load_dwordx4 v[222:225], v[136:137], off nt
	global_load_dwordx4 v[144:147], v[136:137], off offset:256 nt
	global_load_dwordx4 v[226:229], v[138:139], off nt
	global_load_dwordx4 v[148:151], v[138:139], off offset:256 nt
	s_nop 0
	global_load_dwordx4 v[136:139], v[134:135], off nt
	global_load_dwordx4 v[128:131], v[134:135], off offset:256 nt
	global_load_dwordx4 v[140:143], v[230:231], off nt
	s_nop 0
	global_load_dwordx4 v[132:135], v[230:231], off offset:256 nt
	s_andn2_b64 vcc, exec, s[0:1]
	s_mov_b64 s[0:1], -1
	s_waitcnt vmcnt(0)
	v_lshlrev_b32_e32 v234, 16, v194
	v_lshlrev_b32_e32 v230, 16, v190
	v_and_b32_e32 v231, 0xffff0000, v190
	v_and_b32_e32 v235, 0xffff0000, v194
	v_lshlrev_b32_e32 v190, 16, v191
	v_and_b32_e32 v191, 0xffff0000, v191
	v_lshlrev_b32_e32 v194, 16, v195
	v_and_b32_e32 v195, 0xffff0000, v195
	v_lshlrev_b32_e32 v236, 16, v192
	v_and_b32_e32 v237, 0xffff0000, v192
	v_lshlrev_b32_e32 v238, 16, v196
	v_and_b32_e32 v239, 0xffff0000, v196
	v_lshlrev_b32_e32 v192, 16, v193
	v_and_b32_e32 v193, 0xffff0000, v193
	v_lshlrev_b32_e32 v196, 16, v197
	v_and_b32_e32 v197, 0xffff0000, v197
	v_lshlrev_b32_e32 v240, 16, v198
	v_and_b32_e32 v241, 0xffff0000, v198
	v_lshlrev_b32_e32 v242, 16, v202
	v_and_b32_e32 v243, 0xffff0000, v202
	v_lshlrev_b32_e32 v198, 16, v199
	v_and_b32_e32 v199, 0xffff0000, v199
	v_lshlrev_b32_e32 v202, 16, v203
	v_and_b32_e32 v203, 0xffff0000, v203
	v_lshlrev_b32_e32 v244, 16, v200
	v_and_b32_e32 v245, 0xffff0000, v200
	v_lshlrev_b32_e32 v246, 16, v204
	v_and_b32_e32 v247, 0xffff0000, v204
	v_pk_fma_f32 v[124:125], v[124:125], v[234:235], v[230:231]
	v_pk_fma_f32 v[126:127], v[126:127], v[194:195], v[190:191]
	v_pk_fma_f32 v[120:121], v[120:121], v[238:239], v[236:237]
	v_pk_fma_f32 v[122:123], v[122:123], v[196:197], v[192:193]
	v_pk_fma_f32 v[190:191], v[116:117], v[242:243], v[240:241]
	v_pk_fma_f32 v[192:193], v[118:119], v[202:203], v[198:199]
	v_pk_fma_f32 v[108:109], v[108:109], v[246:247], v[244:245]
	v_cvt_pk_bf16_f32 v116, v124, v125
	v_cvt_pk_bf16_f32 v117, v126, v127
	v_cvt_pk_bf16_f32 v118, v120, v121
	v_cvt_pk_bf16_f32 v119, v122, v123
	global_store_dwordx4 v[232:233], v[116:119], off
	v_cvt_pk_bf16_f32 v122, v108, v109
	v_lshlrev_b32_e32 v108, 16, v201
	v_and_b32_e32 v109, 0xffff0000, v201
	v_lshlrev_b32_e32 v116, 16, v205
	v_and_b32_e32 v117, 0xffff0000, v205
	v_pk_fma_f32 v[108:109], v[110:111], v[116:117], v[108:109]
	v_lshlrev_b32_e32 v110, 16, v210
	v_cvt_pk_bf16_f32 v123, v108, v109
	v_lshlrev_b32_e32 v108, 16, v206
	v_and_b32_e32 v109, 0xffff0000, v206
	v_and_b32_e32 v111, 0xffff0000, v210
	v_pk_fma_f32 v[108:109], v[112:113], v[110:111], v[108:109]
	v_lshlrev_b32_e32 v110, 16, v207
	v_and_b32_e32 v111, 0xffff0000, v207
	v_lshlrev_b32_e32 v112, 16, v211
	v_and_b32_e32 v113, 0xffff0000, v211
	v_pk_fma_f32 v[110:111], v[114:115], v[112:113], v[110:111]
	v_cvt_pk_bf16_f32 v108, v108, v109
	v_cvt_pk_bf16_f32 v109, v110, v111
	v_lshlrev_b32_e32 v110, 16, v208
	v_and_b32_e32 v111, 0xffff0000, v208
	v_lshlrev_b32_e32 v112, 16, v212
	v_and_b32_e32 v113, 0xffff0000, v212
	v_pk_fma_f32 v[104:105], v[104:105], v[112:113], v[110:111]
	v_lshlrev_b32_e32 v112, 16, v213
	v_cvt_pk_bf16_f32 v110, v104, v105
	v_lshlrev_b32_e32 v104, 16, v209
	v_and_b32_e32 v105, 0xffff0000, v209
	v_and_b32_e32 v113, 0xffff0000, v213
	v_pk_fma_f32 v[104:105], v[106:107], v[112:113], v[104:105]
	v_lshlrev_b32_e32 v106, 16, v218
	v_cvt_pk_bf16_f32 v111, v104, v105
	v_lshl_add_u64 v[104:105], s[12:13], 0, v[186:187]
	v_lshl_add_u64 v[104:105], v[104:105], 0, v[168:169]
	global_store_dwordx4 v[104:105], v[108:111], off
	v_and_b32_e32 v107, 0xffff0000, v218
	v_cvt_pk_bf16_f32 v120, v190, v191
	v_lshlrev_b32_e32 v108, 16, v214
	v_and_b32_e32 v109, 0xffff0000, v214
	v_pk_fma_f32 v[100:101], v[100:101], v[108:109], v[106:107]
; __device__ __forceinline__ unsigned pk_bf16(float lo, float hi) { typedef __bf16 b2 __attribute__((ext_vector_type(2))); f32x2 v = {lo, hi}; b2 b = __builtin_convertvector(v, b2); return __builtin_bit_cast(unsigned, b); }
; __device__ __forceinline__ float bflo(unsigned u) { return __uint_as_float(u << 16); }
; __device__ __forceinline__ float bfhi(unsigned u) { return __uint_as_float(u & 0xffff0000u); }
;     __device__ __forceinline__ void operator()(const f32x4 (&acc)[2][2][4][2], const Unit& u, int wr, int wc, int fr, int fq) const {
;     ...
;         for (int ai = 0; ai < 2; ++ai) { u32x4 gg[4][2], tb[4][2];
; #pragma unroll
;             for (int m = 0; m < 4; ++m)
; #pragma unroll
;                 for (int bj = 0; bj < 2; ++bj) { const size_t row = row0 + ai * 128 + m * 16; gg[m][bj] = *(const u32x4*)(gates + row * 2048 + col0 + bj * 128); tb[m][bj] = *(const u32x4*)(tmpb + row * 1024 + col0 + bj * 128); }
; #pragma unroll
;             for (int m = 0; m < 4; ++m) { const size_t row = row0 + ai * 128 + m * 16;
; #pragma unroll
;                 for (int bj = 0; bj < 2; ++bj) { const int col = col0 + bj * 128; const u32x4 g = gg[m][bj], t = tb[m][bj];
;                     const f32x4 v0 = acc[ai][bj][m][0], v1 = acc[ai][bj][m][1]; u32x4 w;
;                     w.x = pk_bf16(bflo(t.x) + v0[0] * bflo(g.x), bfhi(t.x) + v0[1] * bfhi(g.x)); w.y = pk_bf16(bflo(t.y) + v0[2] * bflo(g.y), bfhi(t.y) + v0[3] * bfhi(g.y));
;                     w.z = pk_bf16(bflo(t.z) + v1[0] * bflo(g.z), bfhi(t.z) + v1[1] * bfhi(g.z)); w.w = pk_bf16(bflo(t.w) + v1[2] * bflo(g.w), bfhi(t.w) + v1[3] * bfhi(g.w));
;                     *(u32x4*)(merged + row * 1024 + col) = w; } } }
	v_lshlrev_b32_e32 v106, 16, v219
	v_and_b32_e32 v107, 0xffff0000, v219
	v_lshlrev_b32_e32 v108, 16, v215
	v_and_b32_e32 v109, 0xffff0000, v215
	v_pk_fma_f32 v[102:103], v[102:103], v[108:109], v[106:107]
	v_cvt_pk_bf16_f32 v100, v100, v101
	v_cvt_pk_bf16_f32 v101, v102, v103
	v_lshlrev_b32_e32 v102, 16, v220
	v_and_b32_e32 v103, 0xffff0000, v220
	v_lshlrev_b32_e32 v106, 16, v216
	v_and_b32_e32 v107, 0xffff0000, v216
	v_pk_fma_f32 v[92:93], v[92:93], v[106:107], v[102:103]
	v_lshlrev_b32_e32 v106, 16, v217
	v_cvt_pk_bf16_f32 v102, v92, v93
	v_lshlrev_b32_e32 v92, 16, v221
	v_and_b32_e32 v93, 0xffff0000, v221
	v_and_b32_e32 v107, 0xffff0000, v217
	v_pk_fma_f32 v[92:93], v[94:95], v[106:107], v[92:93]
	v_lshlrev_b32_e32 v94, 16, v222
	v_cvt_pk_bf16_f32 v103, v92, v93
	v_lshlrev_b32_e32 v92, 16, v226
	v_and_b32_e32 v93, 0xffff0000, v226
	v_and_b32_e32 v95, 0xffff0000, v222
	v_pk_fma_f32 v[92:93], v[96:97], v[94:95], v[92:93]
	v_lshlrev_b32_e32 v94, 16, v227
	v_and_b32_e32 v95, 0xffff0000, v227
	v_lshlrev_b32_e32 v96, 16, v223
	v_and_b32_e32 v97, 0xffff0000, v223
	v_pk_fma_f32 v[94:95], v[98:99], v[96:97], v[94:95]
	v_cvt_pk_bf16_f32 v92, v92, v93
	v_cvt_pk_bf16_f32 v93, v94, v95
	v_lshlrev_b32_e32 v94, 16, v228
	v_and_b32_e32 v95, 0xffff0000, v228
	v_lshlrev_b32_e32 v96, 16, v224
	v_and_b32_e32 v97, 0xffff0000, v224
	v_pk_fma_f32 v[88:89], v[88:89], v[96:97], v[94:95]
	v_lshlrev_b32_e32 v96, 16, v225
	v_cvt_pk_bf16_f32 v94, v88, v89
	v_lshlrev_b32_e32 v88, 16, v229
	v_and_b32_e32 v89, 0xffff0000, v229
	v_and_b32_e32 v97, 0xffff0000, v225
	v_pk_fma_f32 v[88:89], v[90:91], v[96:97], v[88:89]
	v_lshlrev_b32_e32 v90, 16, v148
	v_cvt_pk_bf16_f32 v95, v88, v89
	v_lshl_add_u64 v[88:89], s[12:13], 0, v[178:179]
	v_lshl_add_u64 v[88:89], v[88:89], 0, v[168:169]
	global_store_dwordx4 v[88:89], v[92:95], off
	v_and_b32_e32 v91, 0xffff0000, v148
	v_cvt_pk_bf16_f32 v121, v192, v193
	v_lshlrev_b32_e32 v92, 16, v144
	v_and_b32_e32 v93, 0xffff0000, v144
	v_pk_fma_f32 v[84:85], v[84:85], v[92:93], v[90:91]
	v_lshlrev_b32_e32 v90, 16, v149
	v_and_b32_e32 v91, 0xffff0000, v149
	v_lshlrev_b32_e32 v92, 16, v145
	v_and_b32_e32 v93, 0xffff0000, v145
	v_pk_fma_f32 v[86:87], v[86:87], v[92:93], v[90:91]
	v_cvt_pk_bf16_f32 v84, v84, v85
	v_cvt_pk_bf16_f32 v85, v86, v87
	v_lshlrev_b32_e32 v86, 16, v150
	v_and_b32_e32 v87, 0xffff0000, v150
	v_lshlrev_b32_e32 v90, 16, v146
	v_and_b32_e32 v91, 0xffff0000, v146
	v_pk_fma_f32 v[76:77], v[76:77], v[90:91], v[86:87]
	v_lshlrev_b32_e32 v90, 16, v147
	v_cvt_pk_bf16_f32 v86, v76, v77
	v_lshlrev_b32_e32 v76, 16, v151
	v_and_b32_e32 v77, 0xffff0000, v151
	v_and_b32_e32 v91, 0xffff0000, v147
	v_pk_fma_f32 v[76:77], v[78:79], v[90:91], v[76:77]
	v_lshlrev_b32_e32 v78, 16, v136
	v_cvt_pk_bf16_f32 v87, v76, v77
	v_lshlrev_b32_e32 v76, 16, v140
	v_and_b32_e32 v77, 0xffff0000, v140
	v_and_b32_e32 v79, 0xffff0000, v136
	v_pk_fma_f32 v[76:77], v[80:81], v[78:79], v[76:77]
	v_lshlrev_b32_e32 v78, 16, v141
	v_and_b32_e32 v79, 0xffff0000, v141
	v_lshlrev_b32_e32 v80, 16, v137
	v_and_b32_e32 v81, 0xffff0000, v137
	v_pk_fma_f32 v[78:79], v[82:83], v[80:81], v[78:79]
	v_cvt_pk_bf16_f32 v76, v76, v77
	v_cvt_pk_bf16_f32 v77, v78, v79
	v_lshlrev_b32_e32 v78, 16, v142
	v_and_b32_e32 v79, 0xffff0000, v142
	v_lshlrev_b32_e32 v80, 16, v138
	v_and_b32_e32 v81, 0xffff0000, v138
	v_pk_fma_f32 v[72:73], v[72:73], v[80:81], v[78:79]
	v_lshlrev_b32_e32 v80, 16, v139
	v_cvt_pk_bf16_f32 v78, v72, v73
	v_lshlrev_b32_e32 v72, 16, v143
	v_and_b32_e32 v73, 0xffff0000, v143
	v_and_b32_e32 v81, 0xffff0000, v139
	v_pk_fma_f32 v[72:73], v[74:75], v[80:81], v[72:73]
	v_lshlrev_b32_e32 v74, 16, v132
	v_cvt_pk_bf16_f32 v79, v72, v73
	v_lshl_add_u64 v[72:73], s[12:13], 0, v[176:177]
	v_lshl_add_u64 v[72:73], v[72:73], 0, v[168:169]
	global_store_dwordx4 v[72:73], v[76:79], off
	v_and_b32_e32 v75, 0xffff0000, v132
	global_store_dwordx4 v[232:233], v[120:123], off offset:256
	v_lshlrev_b32_e32 v76, 16, v128
	v_and_b32_e32 v77, 0xffff0000, v128
	v_pk_fma_f32 v[68:69], v[68:69], v[76:77], v[74:75]
	v_lshlrev_b32_e32 v74, 16, v133
	v_and_b32_e32 v75, 0xffff0000, v133
	v_lshlrev_b32_e32 v76, 16, v129
	v_and_b32_e32 v77, 0xffff0000, v129
	v_pk_fma_f32 v[70:71], v[70:71], v[76:77], v[74:75]
	v_cvt_pk_bf16_f32 v68, v68, v69
	v_cvt_pk_bf16_f32 v69, v70, v71
	v_lshlrev_b32_e32 v70, 16, v134
	v_and_b32_e32 v71, 0xffff0000, v134
	v_lshlrev_b32_e32 v74, 16, v130
	v_and_b32_e32 v75, 0xffff0000, v130
	v_pk_fma_f32 v[64:65], v[64:65], v[74:75], v[70:71]
	v_lshlrev_b32_e32 v74, 16, v131
	v_cvt_pk_bf16_f32 v70, v64, v65
	v_lshlrev_b32_e32 v64, 16, v135
	v_and_b32_e32 v65, 0xffff0000, v135
	v_and_b32_e32 v75, 0xffff0000, v131
	v_pk_fma_f32 v[64:65], v[66:67], v[74:75], v[64:65]
	global_store_dwordx4 v[104:105], v[100:103], off offset:256
	v_cvt_pk_bf16_f32 v71, v64, v65
	v_add_u32_e32 v64, 0x80, v172
	v_ashrrev_i32_e32 v65, 31, v64
	v_lshlrev_b64 v[132:133], 11, v[64:65]
	global_store_dwordx4 v[88:89], v[84:87], off offset:256
	global_store_dwordx4 v[72:73], v[68:71], off offset:256
	v_lshlrev_b64 v[66:67], 12, v[64:65]
	v_lshl_add_u64 v[64:65], v[170:171], 0, v[132:133]
	global_load_dwordx4 v[96:99], v[64:65], off nt
	v_lshl_add_u64 v[66:67], v[174:175], 0, v[66:67]
	global_load_dwordx4 v[100:103], v[66:67], off nt
	global_load_dwordx4 v[104:107], v[64:65], off offset:256 nt
	global_load_dwordx4 v[108:111], v[66:67], off offset:256 nt
	v_add_u32_e32 v64, 0x90, v172
	v_ashrrev_i32_e32 v65, 31, v64
	v_lshlrev_b64 v[134:135], 11, v[64:65]
	v_lshlrev_b64 v[66:67], 12, v[64:65]
	v_lshl_add_u64 v[64:65], v[170:171], 0, v[134:135]
	global_load_dwordx4 v[112:115], v[64:65], off nt
	v_lshl_add_u64 v[66:67], v[174:175], 0, v[66:67]
	global_load_dwordx4 v[116:119], v[66:67], off nt
	global_load_dwordx4 v[120:123], v[66:67], off offset:256 nt
	global_load_dwordx4 v[124:127], v[64:65], off offset:256 nt
	v_add_u32_e32 v64, 0xa0, v172
	v_ashrrev_i32_e32 v65, 31, v64
	v_lshlrev_b64 v[66:67], 12, v[64:65]
	v_lshl_add_u64 v[66:67], v[174:175], 0, v[66:67]
	v_lshlrev_b64 v[94:95], 11, v[64:65]
	v_lshl_add_u64 v[64:65], v[170:171], 0, v[94:95]
	global_load_dwordx4 v[88:91], v[66:67], off nt
	global_load_dwordx4 v[80:83], v[66:67], off offset:256 nt
	global_load_dwordx4 v[128:131], v[64:65], off nt
	global_load_dwordx4 v[84:87], v[64:65], off offset:256 nt
	v_add_u32_e32 v64, 0xb0, v172
	v_ashrrev_i32_e32 v65, 31, v64
	v_lshlrev_b64 v[66:67], 12, v[64:65]
	v_lshlrev_b64 v[92:93], 11, v[64:65]
	v_lshl_add_u64 v[66:67], v[174:175], 0, v[66:67]
	v_lshl_add_u64 v[68:69], v[170:171], 0, v[92:93]
	global_load_dwordx4 v[72:75], v[66:67], off nt
	s_nop 0
	global_load_dwordx4 v[64:67], v[66:67], off offset:256 nt
	s_nop 0
	global_load_dwordx4 v[76:79], v[68:69], off nt
	s_nop 0
	global_load_dwordx4 v[68:71], v[68:69], off offset:256 nt
	s_waitcnt vmcnt(15)
; __device__ __forceinline__ unsigned pk_bf16(float lo, float hi) { typedef __bf16 b2 __attribute__((ext_vector_type(2))); f32x2 v = {lo, hi}; b2 b = __builtin_convertvector(v, b2); return __builtin_bit_cast(unsigned, b); }
; __device__ __forceinline__ float bflo(unsigned u) { return __uint_as_float(u << 16); }
; __device__ __forceinline__ float bfhi(unsigned u) { return __uint_as_float(u & 0xffff0000u); }
;     __device__ __forceinline__ void operator()(const f32x4 (&acc)[2][2][4][2], const Unit& u, int wr, int wc, int fr, int fq) const {
;     ...
;             for (int m = 0; m < 4; ++m) { const size_t row = row0 + ai * 128 + m * 16;
; #pragma unroll
;                 for (int bj = 0; bj < 2; ++bj) { const int col = col0 + bj * 128; const u32x4 g = gg[m][bj], t = tb[m][bj];
;                     const f32x4 v0 = acc[ai][bj][m][0], v1 = acc[ai][bj][m][1]; u32x4 w;
;                     w.x = pk_bf16(bflo(t.x) + v0[0] * bflo(g.x), bfhi(t.x) + v0[1] * bfhi(g.x)); w.y = pk_bf16(bflo(t.y) + v0[2] * bflo(g.y), bfhi(t.y) + v0[3] * bfhi(g.y));
;                     w.z = pk_bf16(bflo(t.z) + v1[0] * bflo(g.z), bfhi(t.z) + v1[1] * bfhi(g.z)); w.w = pk_bf16(bflo(t.w) + v1[2] * bflo(g.w), bfhi(t.w) + v1[3] * bfhi(g.w));
;                     *(u32x4*)(merged + row * 1024 + col) = w; } } }
	v_lshlrev_b32_e32 v136, 16, v96
	v_and_b32_e32 v137, 0xffff0000, v96
	s_waitcnt vmcnt(14)
	v_lshlrev_b32_e32 v138, 16, v100
	v_and_b32_e32 v139, 0xffff0000, v100
	v_lshlrev_b32_e32 v96, 16, v97
	v_and_b32_e32 v97, 0xffff0000, v97
	v_lshlrev_b32_e32 v100, 16, v101
	v_and_b32_e32 v101, 0xffff0000, v101
	v_pk_fma_f32 v[60:61], v[60:61], v[138:139], v[136:137]
	v_pk_fma_f32 v[62:63], v[62:63], v[100:101], v[96:97]
	v_cvt_pk_bf16_f32 v60, v60, v61
	v_cvt_pk_bf16_f32 v61, v62, v63
	v_lshlrev_b32_e32 v62, 16, v98
	v_and_b32_e32 v63, 0xffff0000, v98
	v_lshlrev_b32_e32 v96, 16, v102
	v_and_b32_e32 v97, 0xffff0000, v102
	v_pk_fma_f32 v[56:57], v[56:57], v[96:97], v[62:63]
	v_lshlrev_b32_e32 v96, 16, v103
	v_cvt_pk_bf16_f32 v62, v56, v57
	v_lshlrev_b32_e32 v56, 16, v99
	v_and_b32_e32 v57, 0xffff0000, v99
	v_and_b32_e32 v97, 0xffff0000, v103
	v_pk_fma_f32 v[56:57], v[58:59], v[96:97], v[56:57]
	s_waitcnt vmcnt(13)
	v_lshlrev_b32_e32 v58, 16, v104
	v_cvt_pk_bf16_f32 v63, v56, v57
	v_lshl_add_u64 v[56:57], s[12:13], 0, v[132:133]
	v_lshl_add_u64 v[56:57], v[56:57], 0, v[168:169]
	global_store_dwordx4 v[56:57], v[60:63], off
	v_and_b32_e32 v59, 0xffff0000, v104
	s_waitcnt vmcnt(13)
	v_lshlrev_b32_e32 v60, 16, v108
	v_and_b32_e32 v61, 0xffff0000, v108
	v_pk_fma_f32 v[52:53], v[52:53], v[60:61], v[58:59]
	v_lshlrev_b32_e32 v58, 16, v105
	v_and_b32_e32 v59, 0xffff0000, v105
	v_lshlrev_b32_e32 v60, 16, v109
	v_and_b32_e32 v61, 0xffff0000, v109
	v_pk_fma_f32 v[54:55], v[54:55], v[60:61], v[58:59]
	v_cvt_pk_bf16_f32 v52, v52, v53
	v_cvt_pk_bf16_f32 v53, v54, v55
	v_lshlrev_b32_e32 v54, 16, v106
	v_and_b32_e32 v55, 0xffff0000, v106
	v_lshlrev_b32_e32 v58, 16, v110
	v_and_b32_e32 v59, 0xffff0000, v110
	v_pk_fma_f32 v[44:45], v[44:45], v[58:59], v[54:55]
	v_lshlrev_b32_e32 v58, 16, v111
	v_cvt_pk_bf16_f32 v54, v44, v45
	v_lshlrev_b32_e32 v44, 16, v107
	v_and_b32_e32 v45, 0xffff0000, v107
	v_and_b32_e32 v59, 0xffff0000, v111
	v_pk_fma_f32 v[44:45], v[46:47], v[58:59], v[44:45]
	s_waitcnt vmcnt(11)
	v_lshlrev_b32_e32 v46, 16, v116
	v_cvt_pk_bf16_f32 v55, v44, v45
	v_lshlrev_b32_e32 v44, 16, v112
	v_and_b32_e32 v45, 0xffff0000, v112
	v_and_b32_e32 v47, 0xffff0000, v116
	v_pk_fma_f32 v[44:45], v[48:49], v[46:47], v[44:45]
	v_lshlrev_b32_e32 v46, 16, v113
	v_and_b32_e32 v47, 0xffff0000, v113
	v_lshlrev_b32_e32 v48, 16, v117
	v_and_b32_e32 v49, 0xffff0000, v117
	v_pk_fma_f32 v[46:47], v[50:51], v[48:49], v[46:47]
	v_cvt_pk_bf16_f32 v44, v44, v45
	v_cvt_pk_bf16_f32 v45, v46, v47
	v_lshlrev_b32_e32 v46, 16, v114
	v_and_b32_e32 v47, 0xffff0000, v114
	v_lshlrev_b32_e32 v48, 16, v118
	v_and_b32_e32 v49, 0xffff0000, v118
	v_pk_fma_f32 v[40:41], v[40:41], v[48:49], v[46:47]
	v_lshlrev_b32_e32 v48, 16, v119
	v_cvt_pk_bf16_f32 v46, v40, v41
	v_lshlrev_b32_e32 v40, 16, v115
	v_and_b32_e32 v41, 0xffff0000, v115
	v_and_b32_e32 v49, 0xffff0000, v119
	v_pk_fma_f32 v[40:41], v[42:43], v[48:49], v[40:41]
	s_waitcnt vmcnt(9)
	v_lshlrev_b32_e32 v42, 16, v124
	v_cvt_pk_bf16_f32 v47, v40, v41
	v_lshl_add_u64 v[40:41], s[12:13], 0, v[134:135]
	v_lshl_add_u64 v[40:41], v[40:41], 0, v[168:169]
	global_store_dwordx4 v[40:41], v[44:47], off
	v_and_b32_e32 v43, 0xffff0000, v124
	global_store_dwordx4 v[56:57], v[52:55], off offset:256
	v_lshlrev_b32_e32 v44, 16, v120
	v_and_b32_e32 v45, 0xffff0000, v120
	v_pk_fma_f32 v[36:37], v[36:37], v[44:45], v[42:43]
	v_lshlrev_b32_e32 v42, 16, v125
	v_and_b32_e32 v43, 0xffff0000, v125
	v_lshlrev_b32_e32 v44, 16, v121
	v_and_b32_e32 v45, 0xffff0000, v121
	v_pk_fma_f32 v[38:39], v[38:39], v[44:45], v[42:43]
	v_cvt_pk_bf16_f32 v36, v36, v37
	v_cvt_pk_bf16_f32 v37, v38, v39
	v_lshlrev_b32_e32 v38, 16, v126
	v_and_b32_e32 v39, 0xffff0000, v126
	v_lshlrev_b32_e32 v42, 16, v122
	v_and_b32_e32 v43, 0xffff0000, v122
	v_pk_fma_f32 v[28:29], v[28:29], v[42:43], v[38:39]
	v_lshlrev_b32_e32 v42, 16, v123
	v_cvt_pk_bf16_f32 v38, v28, v29
	v_lshlrev_b32_e32 v28, 16, v127
	v_and_b32_e32 v29, 0xffff0000, v127
	v_and_b32_e32 v43, 0xffff0000, v123
	v_pk_fma_f32 v[28:29], v[30:31], v[42:43], v[28:29]
	s_waitcnt vmcnt(10)
	v_lshlrev_b32_e32 v30, 16, v88
	v_cvt_pk_bf16_f32 v39, v28, v29
	s_waitcnt vmcnt(8)
; __device__ __forceinline__ unsigned pk_bf16(float lo, float hi) { typedef __bf16 b2 __attribute__((ext_vector_type(2))); f32x2 v = {lo, hi}; b2 b = __builtin_convertvector(v, b2); return __builtin_bit_cast(unsigned, b); }
; __device__ __forceinline__ float bflo(unsigned u) { return __uint_as_float(u << 16); }
; __device__ __forceinline__ float bfhi(unsigned u) { return __uint_as_float(u & 0xffff0000u); }
;     __device__ __forceinline__ void operator()(const f32x4 (&acc)[2][2][4][2], const Unit& u, int wr, int wc, int fr, int fq) const {
;     ...
;             for (int m = 0; m < 4; ++m) { const size_t row = row0 + ai * 128 + m * 16;
; #pragma unroll
;                 for (int bj = 0; bj < 2; ++bj) { const int col = col0 + bj * 128; const u32x4 g = gg[m][bj], t = tb[m][bj];
;                     const f32x4 v0 = acc[ai][bj][m][0], v1 = acc[ai][bj][m][1]; u32x4 w;
;                     w.x = pk_bf16(bflo(t.x) + v0[0] * bflo(g.x), bfhi(t.x) + v0[1] * bfhi(g.x)); w.y = pk_bf16(bflo(t.y) + v0[2] * bflo(g.y), bfhi(t.y) + v0[3] * bfhi(g.y));
;                     w.z = pk_bf16(bflo(t.z) + v1[0] * bflo(g.z), bfhi(t.z) + v1[1] * bfhi(g.z)); w.w = pk_bf16(bflo(t.w) + v1[2] * bflo(g.w), bfhi(t.w) + v1[3] * bfhi(g.w));
;                     *(u32x4*)(merged + row * 1024 + col) = w; } } }
	v_lshlrev_b32_e32 v28, 16, v128
	v_and_b32_e32 v29, 0xffff0000, v128
	v_and_b32_e32 v31, 0xffff0000, v88
	v_pk_fma_f32 v[28:29], v[32:33], v[30:31], v[28:29]
	v_lshlrev_b32_e32 v30, 16, v129
	v_and_b32_e32 v31, 0xffff0000, v129
	v_lshlrev_b32_e32 v32, 16, v89
	v_and_b32_e32 v33, 0xffff0000, v89
	v_pk_fma_f32 v[30:31], v[34:35], v[32:33], v[30:31]
	v_cvt_pk_bf16_f32 v28, v28, v29
	v_cvt_pk_bf16_f32 v29, v30, v31
	v_lshlrev_b32_e32 v30, 16, v130
	v_and_b32_e32 v31, 0xffff0000, v130
	v_lshlrev_b32_e32 v32, 16, v90
	v_and_b32_e32 v33, 0xffff0000, v90
	v_pk_fma_f32 v[24:25], v[24:25], v[32:33], v[30:31]
	v_lshlrev_b32_e32 v32, 16, v91
	v_cvt_pk_bf16_f32 v30, v24, v25
	v_lshlrev_b32_e32 v24, 16, v131
	v_and_b32_e32 v25, 0xffff0000, v131
	v_and_b32_e32 v33, 0xffff0000, v91
	v_pk_fma_f32 v[24:25], v[26:27], v[32:33], v[24:25]
	s_waitcnt vmcnt(7)
	v_lshlrev_b32_e32 v26, 16, v84
	v_cvt_pk_bf16_f32 v31, v24, v25
	v_lshl_add_u64 v[24:25], s[12:13], 0, v[94:95]
	v_lshl_add_u64 v[24:25], v[24:25], 0, v[168:169]
	global_store_dwordx4 v[24:25], v[28:31], off
	v_and_b32_e32 v27, 0xffff0000, v84
	global_store_dwordx4 v[40:41], v[36:39], off offset:256
	v_lshlrev_b32_e32 v28, 16, v80
	v_and_b32_e32 v29, 0xffff0000, v80
	v_pk_fma_f32 v[20:21], v[20:21], v[28:29], v[26:27]
	v_lshlrev_b32_e32 v26, 16, v85
	v_and_b32_e32 v27, 0xffff0000, v85
	v_lshlrev_b32_e32 v28, 16, v81
	v_and_b32_e32 v29, 0xffff0000, v81
	v_pk_fma_f32 v[22:23], v[22:23], v[28:29], v[26:27]
	v_cvt_pk_bf16_f32 v20, v20, v21
	v_cvt_pk_bf16_f32 v21, v22, v23
	v_lshlrev_b32_e32 v22, 16, v86
	v_and_b32_e32 v23, 0xffff0000, v86
	v_lshlrev_b32_e32 v26, 16, v82
	v_and_b32_e32 v27, 0xffff0000, v82
	v_pk_fma_f32 v[12:13], v[12:13], v[26:27], v[22:23]
	v_lshlrev_b32_e32 v26, 16, v83
	v_cvt_pk_bf16_f32 v22, v12, v13
	v_lshlrev_b32_e32 v12, 16, v87
	v_and_b32_e32 v13, 0xffff0000, v87
	v_and_b32_e32 v27, 0xffff0000, v83
	v_pk_fma_f32 v[12:13], v[14:15], v[26:27], v[12:13]
	s_waitcnt vmcnt(8)
	v_lshlrev_b32_e32 v14, 16, v72
	v_cvt_pk_bf16_f32 v23, v12, v13
	s_waitcnt vmcnt(6)
	v_lshlrev_b32_e32 v12, 16, v76
	v_and_b32_e32 v13, 0xffff0000, v76
	v_and_b32_e32 v15, 0xffff0000, v72
	v_pk_fma_f32 v[12:13], v[16:17], v[14:15], v[12:13]
	v_lshlrev_b32_e32 v14, 16, v77
	v_and_b32_e32 v15, 0xffff0000, v77
	v_lshlrev_b32_e32 v16, 16, v73
	v_and_b32_e32 v17, 0xffff0000, v73
	v_pk_fma_f32 v[14:15], v[18:19], v[16:17], v[14:15]
	v_cvt_pk_bf16_f32 v12, v12, v13
	v_cvt_pk_bf16_f32 v13, v14, v15
	v_lshlrev_b32_e32 v14, 16, v78
	v_and_b32_e32 v15, 0xffff0000, v78
	v_lshlrev_b32_e32 v16, 16, v74
	v_and_b32_e32 v17, 0xffff0000, v74
	v_pk_fma_f32 v[8:9], v[8:9], v[16:17], v[14:15]
	v_lshlrev_b32_e32 v16, 16, v75
	v_cvt_pk_bf16_f32 v14, v8, v9
	v_lshlrev_b32_e32 v8, 16, v79
	v_and_b32_e32 v9, 0xffff0000, v79
	v_and_b32_e32 v17, 0xffff0000, v75
	v_pk_fma_f32 v[8:9], v[10:11], v[16:17], v[8:9]
	s_waitcnt vmcnt(5)
	v_lshlrev_b32_e32 v10, 16, v68
	v_cvt_pk_bf16_f32 v15, v8, v9
	v_lshl_add_u64 v[8:9], s[12:13], 0, v[92:93]
	v_lshl_add_u64 v[8:9], v[8:9], 0, v[168:169]
	global_store_dwordx4 v[8:9], v[12:15], off
	v_and_b32_e32 v11, 0xffff0000, v68
	global_store_dwordx4 v[24:25], v[20:23], off offset:256
	v_lshlrev_b32_e32 v12, 16, v64
	v_and_b32_e32 v13, 0xffff0000, v64
	v_pk_fma_f32 v[4:5], v[4:5], v[12:13], v[10:11]
	v_lshlrev_b32_e32 v10, 16, v69
	v_and_b32_e32 v11, 0xffff0000, v69
	v_lshlrev_b32_e32 v12, 16, v65
	v_and_b32_e32 v13, 0xffff0000, v65
	v_pk_fma_f32 v[6:7], v[6:7], v[12:13], v[10:11]
	v_cvt_pk_bf16_f32 v4, v4, v5
	v_cvt_pk_bf16_f32 v5, v6, v7
	v_lshlrev_b32_e32 v6, 16, v70
	v_and_b32_e32 v7, 0xffff0000, v70
	v_lshlrev_b32_e32 v10, 16, v66
	v_and_b32_e32 v11, 0xffff0000, v66
	v_pk_fma_f32 v[0:1], v[0:1], v[10:11], v[6:7]
	v_lshlrev_b32_e32 v10, 16, v67
	v_cvt_pk_bf16_f32 v6, v0, v1
	v_lshlrev_b32_e32 v0, 16, v71
	v_and_b32_e32 v1, 0xffff0000, v71
	v_and_b32_e32 v11, 0xffff0000, v67
	v_pk_fma_f32 v[0:1], v[2:3], v[10:11], v[0:1]
	s_nop 0
	v_cvt_pk_bf16_f32 v7, v0, v1
	global_store_dwordx4 v[8:9], v[4:7], off offset:256
	s_cbranch_vccnz .LBB0_596
	s_andn2_b64 vcc, exec, s[6:7]
	s_cbranch_vccnz .LBB0_595
	s_barrier
	s_branch .LBB0_595
